# attention loop fast path made fall-through: rare paths (near-diagonal bias, overflow guard, nsub add, vmcnt(0)) moved out of line; nsub!=0 tracked in an SGPR flag; slimmer vmcnt selection at the tile
# speedup vs baseline: 1.0247x; 1.0247x over previous
; #define LAS __attribute__((address_space(3)))
; __device__ __forceinline__ unsigned cvtpk(float lo, float hi) { f32x2 v = {lo, hi}; bf16x2_t b = __builtin_convertvector(v, bf16x2_t); return __builtin_bit_cast(unsigned, b); }
; #define ATT_WAIT_V(n) asm volatile("s_waitcnt vmcnt(" #n ")" ::: "memory")
; #define ATT_BAR() do { asm volatile("s_waitcnt lgkmcnt(0)" ::: "memory"); __builtin_amdgcn_s_barrier(); asm volatile("" ::: "memory"); } while (0)
; __device__ __forceinline__ float fadd_s(float a, float b) { float r; asm("v_add_f32_e32 %0, %1, %2" : "=v"(r) : "v"(a), "v"(b)); return r; }
; #define ATT_VLD(DST, c) do { _Pragma("unroll") for (int d = 0; d < 4; ++d) DST[d] = *(const LAS bf16x8*)(_vb + d * 4096 + (_xv ^ ((c) << 4))); } while (0)
; __device__ __forceinline__ void sm_exp(f32x16& s, float nsub, float& lsum, unsigned (&pk)[8]) {
;     if (__any(nsub != 0.f)) {
; #pragma unroll
;         for (int r = 0; r < 16; ++r) s[r] += nsub;
;     }
;     float p0 = 0.f, p1 = 0.f, p2 = 0.f, p3 = 0.f;
; #pragma unroll
;     for (int r = 0; r < 16; r += 4) { const float a = __builtin_amdgcn_exp2f(s[r]), b = __builtin_amdgcn_exp2f(s[r + 1]), c = __builtin_amdgcn_exp2f(s[r + 2]), d = __builtin_amdgcn_exp2f(s[r + 3]);
;         p0 = fadd_s(p0, a); p1 = fadd_s(p1, b); p2 = fadd_s(p2, c); p3 = fadd_s(p3, d);
;         pk[r / 2] = cvtpk(a, b); pk[r / 2 + 1] = cvtpk(c, d); }
;     lsum = fadd_s(lsum, fadd_s(fadd_s(p0, p1), fadd_s(p2, p3)));
; }
; __device__ __forceinline__ void attn_unit(const Args& a, LAS unsigned char* lds, float lam, int bh, int qb) {
;     ...
;     for (int t = 0; t < NT; ++t) {
;         if (t + 3 <= NT) ATT_WAIT_V(4); else ATT_WAIT_V(0);
;         ATT_BAR();
;         if (t + 3 < NT) ATT_ISSUE(t + 3, (t + 3) & 3);
;         if (t <= cq) {
;             const bool near = (t >= cq - 2);
;             int _swv = ((l32 >> 1) & 7) << 4; asm volatile("" : "+v"(_swv)); const int _xv = _swv ^ (hi << 4);
;             LAS const unsigned char* _vb = lds + (t & 3) * SLOT + 16384 + l32 * 128;
;             int relb = 64 * t - qrow + 191 + 4 * hi; asm volatile("" : "+v"(relb));
;             LAS const float* tp = tab + relb;
;             bf16x8 va[4], vc[4]; unsigned pk[8];
;             const float ref = 0.f;
;             bf16x8 kn[4];
;             ATT_VLD(va, 0); ATT_VLD(vc, 2); ATT_KLD(t, 1, kn);
.LBB0_519:
	v_exp_f32_e32 v82, v82
	v_exp_f32_e32 v83, v83
	v_exp_f32_e32 v84, v84
	v_exp_f32_e32 v85, v85
	v_add_f32_e32 v146, v161, v82
	v_add_f32_e32 v147, v161, v83
	v_add_f32_e32 v148, v161, v84
	v_add_f32_e32 v149, v161, v85
	v_cvt_pk_bf16_f32 v82, v82, v83
	v_cvt_pk_bf16_f32 v83, v84, v85
	v_exp_f32_e32 v84, v86
	v_exp_f32_e32 v85, v87
	v_exp_f32_e32 v86, v88
	v_exp_f32_e32 v87, v89
	v_add_f32_e32 v88, v146, v84
	v_add_f32_e32 v89, v147, v85
	v_add_f32_e32 v146, v148, v86
	v_add_f32_e32 v147, v149, v87
	v_cvt_pk_bf16_f32 v84, v84, v85
	v_cvt_pk_bf16_f32 v85, v86, v87
	v_exp_f32_e32 v86, v90
	v_exp_f32_e32 v87, v91
	v_exp_f32_e32 v90, v92
	v_exp_f32_e32 v91, v93
	v_add_f32_e32 v88, v88, v86
	v_add_f32_e32 v89, v89, v87
	v_add_f32_e32 v92, v146, v90
	v_add_f32_e32 v93, v147, v91
	v_cvt_pk_bf16_f32 v86, v86, v87
	v_cvt_pk_bf16_f32 v87, v90, v91
	v_exp_f32_e32 v90, v94
	v_exp_f32_e32 v91, v95
	v_exp_f32_e32 v94, v96
	v_exp_f32_e32 v95, v97
	v_add_f32_e32 v96, v88, v90
	v_add_f32_e32 v97, v89, v91
	v_cvt_pk_bf16_f32 v88, v90, v91
	v_add_f32_e32 v90, v96, v97
	s_max_u32 s2, s69, 1
	v_add_f32_e32 v92, v92, v94
	v_add_f32_e32 v93, v93, v95
	v_cvt_pk_bf16_f32 v89, v94, v95
	v_add_f32_e32 v91, v92, v93
	s_nop 0
	v_add_f32_e32 v90, v90, v91
	s_nop 0
	v_add_f32_e32 v228, v208, v90
	v_mfma_f32_32x32x16_bf16 v[18:33], v[82:85], v[142:145], v[18:33]
	v_mfma_f32_32x32x16_bf16 v[34:49], v[82:85], v[138:141], v[34:49]
	v_mfma_f32_32x32x16_bf16 v[50:65], v[82:85], v[134:137], v[50:65]
	v_mfma_f32_32x32x16_bf16 v[2:17], v[82:85], v[130:133], v[2:17]
	v_mfma_f32_32x32x16_bf16 v[18:33], v[86:89], v[126:129], v[18:33]
	v_mfma_f32_32x32x16_bf16 v[34:49], v[86:89], v[122:125], v[34:49]
	v_mfma_f32_32x32x16_bf16 v[50:65], v[86:89], v[118:121], v[50:65]
	v_mfma_f32_32x32x16_bf16 v[2:17], v[86:89], v[114:117], v[2:17]
	s_cmp_eq_u32 s2, 1
	s_cbranch_scc1 .LBB0_543
	v_lshl_add_u32 v82, s73, 7, v221
	s_lshl_b32 s73, s73, 1
	s_add_i32 s72, s70, -2
	v_subrev_u32_e32 v227, s66, v82
	s_addk_i32 s73, 0xff01
	s_mov_b32 s74, 4
	s_movk_i32 s14, 0x100
	s_mov_b32 s75, 0x10000
	v_mov_b64_e32 v[206:207], v[204:205]
	v_xor_b32_e32 v229, v212, v213
	v_sub_f32_e32 v208, 0, v226
	v_cmp_neq_f32_e32 vcc, 0, v226
	s_nop 1
	s_cmp_lg_u64 vcc, 0
	s_cselect_b32 s98, 1, 0
	s_add_i32 s76, s68, 0x8000
	v_add_u32_e32 v240, 0x8000, v214
	v_add_u32_e32 v241, s76, v214
	v_xad_u32 v242, v212, v213, v241
	v_xad_u32 v243, v212, v217, v241
	v_xad_u32 v244, v212, v218, v241
	v_xad_u32 v245, v212, v219, v241
	v_add_u32_e32 v246, v240, v229
	v_xad_u32 v241, v229, 32, v240
	ds_read_b128 v[252:255], v242 offset:4096
	ds_read_b128 v[150:153], v243 offset:4096
	ds_read_b128 v[154:157], v244 offset:4096
	ds_read_b128 v[146:149], v245 offset:4096
	ds_read_b128 v[142:145], v246 offset:16384
	ds_read_b128 v[138:141], v246 offset:20480
	ds_read_b128 v[134:137], v246 offset:24576
	ds_read_b128 v[126:129], v246 offset:28672
	ds_read_b128 v[130:133], v241 offset:16384
	ds_read_b128 v[122:125], v241 offset:20480
	ds_read_b128 v[118:121], v241 offset:24576
	ds_read_b128 v[114:117], v241 offset:28672
	s_branch .LBB0_523

; #define LAS __attribute__((address_space(3)))
; #define ATT_WAIT_V(n) asm volatile("s_waitcnt vmcnt(" #n ")" ::: "memory")
; #define ATT_BAR() do { asm volatile("s_waitcnt lgkmcnt(0)" ::: "memory"); __builtin_amdgcn_s_barrier(); asm volatile("" ::: "memory"); } while (0)
; #define ATT_KLD(tt, blk, KN) do { \
;         int _sw = ((l32 >> 1) & 7) << 4; asm volatile("" : "+v"(_sw)); const int _xo = _sw ^ (hi << 4); \
;         LAS const unsigned char* _kb = lds + ((tt) & 3) * SLOT + mp * 8192 + (blk) * 4096 + l32 * 128; \
;         _Pragma("unroll") for (int d0 = 0; d0 < 4; ++d0) KN[d0] = *(const LAS bf16x8*)(_kb + (_xo ^ (d0 << 5))); } while (0)
; #define ATT_SMM(KN, S) do { S = MFMA32(KN[0], qf[0], ((f32x16){})); _Pragma("unroll") for (int d0 = 1; d0 < 4; ++d0) S = MFMA32(KN[d0], qf[d0], S); } while (0)
; #define ATT_VLD(DST, c) do { _Pragma("unroll") for (int d = 0; d < 4; ++d) DST[d] = *(const LAS bf16x8*)(_vb + d * 4096 + (_xv ^ ((c) << 4))); } while (0)
; #define ATT_FENCE() __builtin_amdgcn_sched_barrier(0)
; #define SCHED_A() do {} while (0)
; __device__ __forceinline__ void attn_unit(const Args& a, LAS unsigned char* lds, float lam, int bh, int qb) {
;     ...
;     for (int t = 0; t < NT; ++t) {
;         if (t + 3 <= NT) ATT_WAIT_V(4); else ATT_WAIT_V(0);
;         ATT_BAR();
;         if (t + 3 < NT) ATT_ISSUE(t + 3, (t + 3) & 3);
;         if (t <= cq) {
;             const bool near = (t >= cq - 2);
;             int _swv = ((l32 >> 1) & 7) << 4; asm volatile("" : "+v"(_swv)); const int _xv = _swv ^ (hi << 4);
;             LAS const unsigned char* _vb = lds + (t & 3) * SLOT + 16384 + l32 * 128;
;             int relb = 64 * t - qrow + 191 + 4 * hi; asm volatile("" : "+v"(relb));
;             LAS const float* tp = tab + relb;
;             bf16x8 va[4], vc[4]; unsigned pk[8];
;             const float ref = 0.f;
;             bf16x8 kn[4];
;             ATT_VLD(va, 0); ATT_VLD(vc, 2); ATT_KLD(t, 1, kn);
;             const float nsX = sm_pre(sX, near, tp, ref, t == 0, (t & 3) == 0, mhat, lsum, o, wsf, l32, hi);
;             ATT_FENCE();
;             ATT_SMM(kn, sY);
;             sm_exp(sX, nsX, lsum, pk);
;             SCHED_A();
;             ATT_FENCE();
;             ATT_PV1(pk, 0, va); ATT_PV1(pk, 1, vc);
;             ATT_FENCE();
;             ATT_VLD(va, 4); ATT_VLD(vc, 6); ATT_KLD(t + 1, 0, kn);
.LBB0_523:
	s_cmp_gt_u32 s74, s69
	s_cbranch_scc1 .Latt_vm0
	s_waitcnt vmcnt(4)
.Latt_vm_done:
	s_waitcnt lgkmcnt(12)
	s_barrier
	s_add_i32 s9, s74, -3
	s_cmp_gt_u32 s9, s70
	s_cbranch_scc1 .LBB0_522
	s_and_b32 s8, s9, 3
	s_lshl_b32 s76, s8, 15
	v_add_u32_e32 v231, s76, v214
	s_and_b32 s76, s75, 0x18000
	v_xad_u32 v240, v229, 64, v231
	v_xad_u32 v241, v229, s42, v231
	v_add_u32_e32 v242, s76, v169
	v_xad_u32 v243, v212, v213, v242
	v_xad_u32 v244, v212, v217, v242
	v_xad_u32 v245, v212, v218, v242
	v_xad_u32 v246, v212, v219, v242
	s_cmp_ge_i32 s9, s72
	s_cselect_b64 s[2:3], -1, 0
	s_cbranch_scc1 .Latt_near_a
.Latt_near_a_done:
	s_cmp_eq_u32 s8, 0
	s_cbranch_scc1 .Latt_guard
.LBB0_537:
	s_cmp_lg_u32 s98, 0
	s_cbranch_scc1 .Latt_nsub_a
.Latt_fast_a:
	s_waitcnt lgkmcnt(8)
	v_mfma_f32_32x32x16_bf16 v[82:97], v[252:255], v[98:101], 0
	v_exp_f32_e32 v66, v66
	v_exp_f32_e32 v67, v67
	v_exp_f32_e32 v68, v68
	v_mfma_f32_32x32x16_bf16 v[82:97], v[150:153], v[102:105], v[82:97]
	v_exp_f32_e32 v69, v69
	v_exp_f32_e32 v70, v70
	v_exp_f32_e32 v71, v71
	v_mfma_f32_32x32x16_bf16 v[82:97], v[154:157], v[106:109], v[82:97]
	v_exp_f32_e32 v72, v72
	v_exp_f32_e32 v73, v73
	v_add_f32_e32 v247, v66, v70
	v_add_f32_e32 v248, v67, v71
	v_mfma_f32_32x32x16_bf16 v[82:97], v[146:149], v[110:113], v[82:97]
	v_add_f32_e32 v249, v68, v72
	v_add_f32_e32 v250, v69, v73
	v_cvt_pk_bf16_f32 v66, v66, v67
	v_cvt_pk_bf16_f32 v67, v68, v69
	v_cvt_pk_bf16_f32 v68, v70, v71
	v_cvt_pk_bf16_f32 v69, v72, v73
	v_exp_f32_e32 v74, v74
	v_exp_f32_e32 v75, v75
	s_waitcnt lgkmcnt(0)
	v_mfma_f32_32x32x16_bf16 v[18:33], v[66:69], v[142:145], v[18:33]
	v_exp_f32_e32 v76, v76
	v_exp_f32_e32 v77, v77
	ds_read_b128 v[252:255], v243
	ds_read_b128 v[150:153], v244
	v_mfma_f32_32x32x16_bf16 v[34:49], v[66:69], v[138:141], v[34:49]
	v_add_f32_e32 v247, v247, v74
	v_add_f32_e32 v248, v248, v75
	v_add_f32_e32 v249, v249, v76
	v_add_f32_e32 v250, v250, v77
	v_cvt_pk_bf16_f32 v70, v74, v75
	v_cvt_pk_bf16_f32 v71, v76, v77
	ds_read_b128 v[154:157], v245
	ds_read_b128 v[146:149], v246
	ds_read_b128 v[142:145], v240 offset:16384
	v_mfma_f32_32x32x16_bf16 v[50:65], v[66:69], v[134:137], v[50:65]
	v_exp_f32_e32 v78, v78
	v_exp_f32_e32 v79, v79
	v_exp_f32_e32 v80, v80
	ds_read_b128 v[138:141], v240 offset:20480
	v_mfma_f32_32x32x16_bf16 v[2:17], v[66:69], v[126:129], v[2:17]
	v_exp_f32_e32 v81, v81
	v_add_f32_e32 v247, v247, v78
	v_add_f32_e32 v248, v248, v79
	v_add_f32_e32 v249, v249, v80
	v_add_f32_e32 v250, v250, v81
	v_cvt_pk_bf16_f32 v72, v78, v79
	v_cvt_pk_bf16_f32 v73, v80, v81
	v_add_f32_e32 v247, v247, v248
	v_add_f32_e32 v249, v249, v250
	ds_read_b128 v[134:137], v240 offset:24576
	s_add_i32 s76, s75, 0x10000
	s_and_b32 s76, s76, 0x18000
	s_add_i32 s76, s67, s76
	s_cmp_ge_u32 s74, s69
	s_cbranch_scc1 .Latt_tail_nodma
	v_mfma_f32_32x32x16_bf16 v[18:33], v[70:73], v[130:133], v[18:33]
	v_add_f32_e32 v247, v247, v249
	v_add_f32_e32 v228, v228, v247
	ds_read_b128 v[126:129], v241 offset:16384
	v_lshl_add_u64 v[232:233], v[206:207], 0, s[28:29]
	s_mov_b32 m0, s76
	v_lshl_add_u64 v[234:235], s[14:15], 1, v[174:175]
	global_load_lds_dwordx4 v[232:233], off
	v_mfma_f32_32x32x16_bf16 v[34:49], v[70:73], v[122:125], v[34:49]
	ds_read_b128 v[130:133], v240 offset:28672
	s_add_i32 m0, s76, 0x2000
	s_nop 0
	global_load_lds_dwordx4 v[206:207], off
	v_mfma_f32_32x32x16_bf16 v[50:65], v[70:73], v[118:121], v[50:65]
	ds_read_b128 v[122:125], v241 offset:20480
	s_add_i32 m0, s76, 0x4000
	s_nop 0
	global_load_lds_dwordx4 v[234:235], off
	v_lshl_add_u64 v[234:235], v[234:235], 0, s[18:19]
	v_mfma_f32_32x32x16_bf16 v[2:17], v[70:73], v[114:117], v[2:17]
	ds_read_b128 v[118:121], v241 offset:24576
	ds_read_b128 v[114:117], v241 offset:28672
	s_add_i32 m0, s76, 0x6000
	s_nop 0
	global_load_lds_dwordx4 v[234:235], off
.Latt_half_b:
	s_cmp_lg_u64 s[2:3], 0
	s_cbranch_scc1 .Latt_near_b

; #define ATT_KLD(tt, blk, KN) do { \
;         int _sw = ((l32 >> 1) & 7) << 4; asm volatile("" : "+v"(_sw)); const int _xo = _sw ^ (hi << 4); \
;         LAS const unsigned char* _kb = lds + ((tt) & 3) * SLOT + mp * 8192 + (blk) * 4096 + l32 * 128; \
;         _Pragma("unroll") for (int d0 = 0; d0 < 4; ++d0) KN[d0] = *(const LAS bf16x8*)(_kb + (_xo ^ (d0 << 5))); } while (0)
; #define ATT_SMM(KN, S) do { S = MFMA32(KN[0], qf[0], ((f32x16){})); _Pragma("unroll") for (int d0 = 1; d0 < 4; ++d0) S = MFMA32(KN[d0], qf[d0], S); } while (0)
; #define ATT_VLD(DST, c) do { _Pragma("unroll") for (int d = 0; d < 4; ++d) DST[d] = *(const LAS bf16x8*)(_vb + d * 4096 + (_xv ^ ((c) << 4))); } while (0)
; #define ATT_PV1(PK, jj, VF) do { const bf16x8 _P = __builtin_bit_cast(bf16x8, (u32x4){PK[4 * (jj)], PK[4 * (jj) + 1], PK[4 * (jj) + 2], PK[4 * (jj) + 3]}); \
;         _Pragma("unroll") for (int d = 0; d < 4; ++d) o[d] = MFMA32(_P, VF[d], o[d]); } while (0)
; #define ATT_FENCE() __builtin_amdgcn_sched_barrier(0)
; #define SCHED_A() do { _Pragma("unroll") for (int _i = 0; _i < 4; ++_i) { __builtin_amdgcn_sched_group_barrier(0x008, 1, 0); __builtin_amdgcn_sched_group_barrier(0x002, 12, 0); } } while (0)
; #define SCHED_A() do {} while (0)
; __device__ __forceinline__ float sm_pre(f32x16& s, bool near, LAS const float* tp, float ref, bool first, bool guard, float& mhat, float& lsum, f32x16 (&o)[4], LAS float* wsf, int l32, int hi) {
;     if (near) {
; #pragma unroll
;         for (int r = 0; r < 16; ++r) s[r] += tp[(r & 3) + 8 * (r >> 2)];
;     }
; __device__ __forceinline__ void attn_unit(const Args& a, LAS unsigned char* lds, float lam, int bh, int qb) {
;     ...
;             ATT_VLD(va, 4); ATT_VLD(vc, 6); ATT_KLD(t + 1, 0, kn);
;             const float nsY = sm_pre(sY, near, tp + 32, ref, false, false, mhat, lsum, o, wsf, l32, hi);
;             ATT_FENCE();
;             ATT_SMM(kn, sX);
;             sm_exp(sY, nsY, lsum, pk);
;             SCHED_A();
;             ATT_FENCE();
;             ATT_PV1(pk, 0, va); ATT_PV1(pk, 1, vc);
;             ATT_FENCE();
.Latt_fast_b:
	s_add_i32 s76, s74, -2
	s_and_b32 s76, s76, 3
	s_lshl_b32 s76, s76, 15
	v_add_u32_e32 v240, s76, v214
	s_add_i32 s76, s76, s68
	v_add_u32_e32 v241, s76, v214
	v_xad_u32 v242, v212, v213, v241
	v_xad_u32 v243, v212, v217, v241
	v_xad_u32 v244, v212, v218, v241
	v_xad_u32 v245, v212, v219, v241
	v_add_u32_e32 v246, v240, v229
	v_xad_u32 v241, v229, 32, v240
	s_waitcnt lgkmcnt(8)
	v_mfma_f32_32x32x16_bf16 v[66:81], v[252:255], v[98:101], 0
	v_exp_f32_e32 v82, v82
	v_exp_f32_e32 v83, v83
	v_exp_f32_e32 v84, v84
	v_mfma_f32_32x32x16_bf16 v[66:81], v[150:153], v[102:105], v[66:81]
	v_exp_f32_e32 v85, v85
	v_exp_f32_e32 v86, v86
	v_exp_f32_e32 v87, v87
	ds_read_b128 v[252:255], v242 offset:4096
	v_mfma_f32_32x32x16_bf16 v[66:81], v[154:157], v[106:109], v[66:81]
	v_exp_f32_e32 v88, v88
	v_exp_f32_e32 v89, v89
	v_add_f32_e32 v247, v82, v86
	v_add_f32_e32 v248, v83, v87
	ds_read_b128 v[150:153], v243 offset:4096
	v_mfma_f32_32x32x16_bf16 v[66:81], v[146:149], v[110:113], v[66:81]
	v_add_f32_e32 v249, v84, v88
	v_add_f32_e32 v250, v85, v89
	v_cvt_pk_bf16_f32 v82, v82, v83
	v_cvt_pk_bf16_f32 v83, v84, v85
	v_cvt_pk_bf16_f32 v84, v86, v87
	v_cvt_pk_bf16_f32 v85, v88, v89
	v_exp_f32_e32 v90, v90
	v_exp_f32_e32 v91, v91
	ds_read_b128 v[154:157], v244 offset:4096
	s_waitcnt lgkmcnt(3)
	v_mfma_f32_32x32x16_bf16 v[18:33], v[82:85], v[142:145], v[18:33]
	v_exp_f32_e32 v92, v92
	v_exp_f32_e32 v93, v93
	ds_read_b128 v[146:149], v245 offset:4096
	v_mfma_f32_32x32x16_bf16 v[34:49], v[82:85], v[138:141], v[34:49]
	v_add_f32_e32 v247, v247, v90
	v_add_f32_e32 v248, v248, v91
	v_add_f32_e32 v249, v249, v92
	v_add_f32_e32 v250, v250, v93
	v_cvt_pk_bf16_f32 v86, v90, v91
	v_cvt_pk_bf16_f32 v87, v92, v93
	ds_read_b128 v[142:145], v246 offset:16384
	v_mfma_f32_32x32x16_bf16 v[50:65], v[82:85], v[134:137], v[50:65]
	v_exp_f32_e32 v94, v94
	v_exp_f32_e32 v95, v95
	v_exp_f32_e32 v96, v96
	ds_read_b128 v[138:141], v246 offset:20480
	v_mfma_f32_32x32x16_bf16 v[2:17], v[82:85], v[130:133], v[2:17]
	v_exp_f32_e32 v97, v97
	v_add_f32_e32 v247, v247, v94
	v_add_f32_e32 v248, v248, v95
	v_add_f32_e32 v249, v249, v96
	v_add_f32_e32 v250, v250, v97
	v_cvt_pk_bf16_f32 v88, v94, v95
	v_cvt_pk_bf16_f32 v89, v96, v97
	v_add_f32_e32 v247, v247, v248
	v_add_f32_e32 v249, v249, v250
	ds_read_b128 v[134:137], v246 offset:24576
	v_mfma_f32_32x32x16_bf16 v[18:33], v[86:89], v[126:129], v[18:33]
	v_add_f32_e32 v247, v247, v249
	v_add_f32_e32 v228, v228, v247
	ds_read_b128 v[130:133], v241 offset:16384
	v_mfma_f32_32x32x16_bf16 v[34:49], v[86:89], v[122:125], v[34:49]
	ds_read_b128 v[126:129], v246 offset:28672
	v_mfma_f32_32x32x16_bf16 v[50:65], v[86:89], v[118:121], v[50:65]
	ds_read_b128 v[122:125], v241 offset:20480
	v_mfma_f32_32x32x16_bf16 v[2:17], v[86:89], v[114:117], v[2:17]
	ds_read_b128 v[118:121], v241 offset:24576
	ds_read_b128 v[114:117], v241 offset:28672
	s_branch .LBB0_522
.Latt_vm0:
	s_waitcnt vmcnt(0)
	s_branch .Latt_vm_done
.Latt_near_a:
	v_add_u32_e32 v86, s14, v227
	v_add_u32_e32 v86, 0xffffc07f, v86
	v_lshl_add_u32 v230, v86, 2, s41
	ds_read2_b32 v[86:87], v230 offset1:1
	ds_read2_b32 v[88:89], v230 offset0:16 offset1:17
	ds_read2_b32 v[90:91], v230 offset0:18 offset1:19
	ds_read2_b32 v[92:93], v230 offset0:24 offset1:25
	ds_read2_b32 v[94:95], v230 offset0:26 offset1:27
	ds_read2_b32 v[96:97], v230 offset0:2 offset1:3
	ds_read2_b32 v[232:233], v230 offset0:8 offset1:9
	ds_read2_b32 v[234:235], v230 offset0:10 offset1:11
	s_waitcnt lgkmcnt(0)
	v_pk_add_f32 v[66:67], v[66:67], v[86:87]
	v_pk_add_f32 v[80:81], v[80:81], v[94:95]
	v_pk_add_f32 v[78:79], v[78:79], v[92:93]
	v_pk_add_f32 v[76:77], v[76:77], v[90:91]
	v_pk_add_f32 v[74:75], v[74:75], v[88:89]
	v_pk_add_f32 v[72:73], v[72:73], v[234:235]
	v_pk_add_f32 v[70:71], v[70:71], v[232:233]
	v_pk_add_f32 v[68:69], v[68:69], v[96:97]
	s_branch .Latt_near_a_done
; #define LAS __attribute__((address_space(3)))
; __device__ __forceinline__ float max3f(float a, float b, float c) { float r; asm("v_max3_f32 %0, %1, %2, %3" : "=v"(r) : "v"(a), "v"(b), "v"(c)); return r; }
; __device__ __forceinline__ float sm_pre(f32x16& s, bool near, LAS const float* tp, float ref, bool first, bool guard, float& mhat, float& lsum, f32x16 (&o)[4], LAS float* wsf, int l32, int hi) {
;     ...
;     if (guard) {
;     float rm = max3f(s[0], s[1], s[2]); float rm2 = max3f(s[3], s[4], s[5]);
;     rm = max3f(rm, s[6], s[7]); rm2 = max3f(rm2, s[8], s[9]); rm = max3f(rm, s[10], s[11]); rm2 = max3f(rm2, s[12], s[13]); rm = max3f(rm, s[14], s[15]);
;     rm = max3f(rm, rm2, rm2);
;     { auto rr = __builtin_amdgcn_permlane32_swap(__float_as_uint(rm), __float_as_uint(rm), false, false); rm = max3f(__uint_as_float(rr[0]), __uint_as_float(rr[1]), rm); }
;     rm += ref - mhat;
;     if (__any(rm > THR)) {
;         const float dl = fmaxf(rm, 0.f);
;         mhat += dl;
;         {
;             const float f = __builtin_amdgcn_exp2f(-dl);
;             lsum *= f;
;             if (hi == 0) wsf[l32] = f;
;             asm volatile("s_waitcnt lgkmcnt(0)" ::: "memory");
; #pragma unroll
;             for (int r4 = 0; r4 < 4; ++r4) { const f32x4 fv = *(const LAS f32x4*)(wsf + 8 * r4 + 4 * hi);
; #pragma unroll
;                 for (int d = 0; d < 4; ++d) { o[d][4 * r4] *= fv[0]; o[d][4 * r4 + 1] *= fv[1]; o[d][4 * r4 + 2] *= fv[2]; o[d][4 * r4 + 3] *= fv[3]; } }
;             asm volatile("s_waitcnt lgkmcnt(0)" ::: "memory");
;         }
;     }
;     }
;     return ref - mhat;
; }
; __device__ __forceinline__ float fadd_s(float a, float b) { float r; asm("v_add_f32_e32 %0, %1, %2" : "=v"(r) : "v"(a), "v"(b)); return r; }
; __device__ __forceinline__ void sm_exp(f32x16& s, float nsub, float& lsum, unsigned (&pk)[8]) {
;     if (__any(nsub != 0.f)) {
; #pragma unroll
;         for (int r = 0; r < 16; ++r) s[r] += nsub;
;     }
.Latt_guard:
	v_max3_f32 v86, v66, v67, v68
	v_max3_f32 v87, v69, v70, v71
	s_nop 0
	v_max3_f32 v86, v86, v72, v73
	v_max3_f32 v87, v87, v74, v75
	s_nop 0
	v_max3_f32 v86, v86, v76, v77
	v_max3_f32 v87, v87, v78, v79
	s_nop 0
	v_max3_f32 v86, v86, v80, v81
	s_nop 0
	v_max3_f32 v86, v86, v87, v87
	s_nop 0
	v_mov_b32_e32 v87, v86
	v_mov_b32_e32 v88, v86
	s_nop 1
	v_permlane32_swap_b32_e32 v87, v88
	v_max3_f32 v86, v87, v88, v86
	s_nop 0
	v_add_f32_e64 v86, -v226, v86
	v_cmp_lt_f32_e32 vcc, s53, v86
	s_cbranch_vccz .LBB0_537
	v_max_f32_e32 v86, v86, v86
	v_max_f32_e32 v86, 0, v86
	v_exp_f32_e64 v87, -v86
	s_and_saveexec_b64 s[8:9], s[6:7]
	ds_write_b32 v225, v87
	s_or_b64 exec, exec, s[8:9]
	s_waitcnt lgkmcnt(0)
	v_add_u32_e32 v208, s71, v213
	v_add_f32_e32 v226, v226, v86
	v_mul_f32_e32 v228, v228, v87
	ds_read_b128 v[86:89], v208
	ds_read_b128 v[90:93], v208 offset:32
	ds_read_b128 v[94:97], v208 offset:64
	ds_read_b128 v[232:235], v208 offset:96
	s_waitcnt lgkmcnt(0)
	s_waitcnt lgkmcnt(0)
	v_pk_mul_f32 v[20:21], v[20:21], v[88:89]
	v_pk_mul_f32 v[22:23], v[22:23], v[90:91]
	v_pk_mul_f32 v[26:27], v[26:27], v[94:95]
	v_pk_mul_f32 v[30:31], v[30:31], v[232:233]
	v_pk_mul_f32 v[32:33], v[32:33], v[234:235]
	v_pk_mul_f32 v[28:29], v[28:29], v[96:97]
	v_pk_mul_f32 v[24:25], v[24:25], v[92:93]
	v_pk_mul_f32 v[18:19], v[18:19], v[86:87]
	v_pk_mul_f32 v[46:47], v[46:47], v[232:233]
	v_pk_mul_f32 v[42:43], v[42:43], v[94:95]
	v_pk_mul_f32 v[38:39], v[38:39], v[90:91]
	v_pk_mul_f32 v[48:49], v[48:49], v[234:235]
	v_pk_mul_f32 v[44:45], v[44:45], v[96:97]
	v_pk_mul_f32 v[40:41], v[40:41], v[92:93]
	v_pk_mul_f32 v[36:37], v[36:37], v[88:89]
	v_pk_mul_f32 v[34:35], v[34:35], v[86:87]
	v_pk_mul_f32 v[62:63], v[62:63], v[232:233]
	v_pk_mul_f32 v[58:59], v[58:59], v[94:95]
	v_pk_mul_f32 v[54:55], v[54:55], v[90:91]
	v_pk_mul_f32 v[64:65], v[64:65], v[234:235]
	v_pk_mul_f32 v[60:61], v[60:61], v[96:97]
	v_pk_mul_f32 v[56:57], v[56:57], v[92:93]
	v_pk_mul_f32 v[52:53], v[52:53], v[88:89]
	v_pk_mul_f32 v[50:51], v[50:51], v[86:87]
	v_pk_mul_f32 v[14:15], v[14:15], v[232:233]
	v_pk_mul_f32 v[10:11], v[10:11], v[94:95]
	v_pk_mul_f32 v[6:7], v[6:7], v[90:91]
	v_pk_mul_f32 v[16:17], v[16:17], v[234:235]
	v_pk_mul_f32 v[12:13], v[12:13], v[96:97]
	v_pk_mul_f32 v[8:9], v[8:9], v[92:93]
	v_pk_mul_f32 v[4:5], v[4:5], v[88:89]
	v_pk_mul_f32 v[2:3], v[2:3], v[86:87]
	v_sub_f32_e32 v208, 0, v226
	s_mov_b32 s98, 1
	s_branch .LBB0_537
.Latt_nsub_a:
	v_pk_add_f32 v[80:81], v[80:81], v[208:209] op_sel_hi:[1,0]
	v_pk_add_f32 v[78:79], v[78:79], v[208:209] op_sel_hi:[1,0]
	v_pk_add_f32 v[76:77], v[76:77], v[208:209] op_sel_hi:[1,0]
	v_pk_add_f32 v[74:75], v[74:75], v[208:209] op_sel_hi:[1,0]
	v_pk_add_f32 v[72:73], v[72:73], v[208:209] op_sel_hi:[1,0]
	v_pk_add_f32 v[70:71], v[70:71], v[208:209] op_sel_hi:[1,0]
	v_pk_add_f32 v[68:69], v[68:69], v[208:209] op_sel_hi:[1,0]
	v_pk_add_f32 v[66:67], v[66:67], v[208:209] op_sel_hi:[1,0]
	s_nop 0
	s_branch .Latt_fast_a
.Latt_tail_nodma:
	v_mfma_f32_32x32x16_bf16 v[18:33], v[70:73], v[130:133], v[18:33]
	v_add_f32_e32 v247, v247, v249
	v_add_f32_e32 v228, v228, v247
	ds_read_b128 v[126:129], v241 offset:16384
	v_mfma_f32_32x32x16_bf16 v[34:49], v[70:73], v[122:125], v[34:49]
	ds_read_b128 v[130:133], v240 offset:28672
	v_mfma_f32_32x32x16_bf16 v[50:65], v[70:73], v[118:121], v[50:65]
	ds_read_b128 v[122:125], v241 offset:20480
	v_mfma_f32_32x32x16_bf16 v[2:17], v[70:73], v[114:117], v[2:17]
	ds_read_b128 v[118:121], v241 offset:24576
	ds_read_b128 v[114:117], v241 offset:28672
	s_branch .Latt_half_b
.Latt_near_b:
	ds_read2_b32 v[240:241], v230 offset0:32 offset1:33
	ds_read2_b32 v[242:243], v230 offset0:48 offset1:49
	ds_read2_b32 v[74:75], v230 offset0:50 offset1:51
	ds_read2_b32 v[76:77], v230 offset0:56 offset1:57
	ds_read2_b32 v[78:79], v230 offset0:58 offset1:59
	ds_read2_b32 v[80:81], v230 offset0:34 offset1:35
	ds_read2_b32 v[232:233], v230 offset0:40 offset1:41
	ds_read2_b32 v[230:231], v230 offset0:42 offset1:43
	s_waitcnt lgkmcnt(0)
	v_pk_add_f32 v[82:83], v[82:83], v[240:241]
	v_pk_add_f32 v[96:97], v[96:97], v[78:79]
	v_pk_add_f32 v[94:95], v[94:95], v[76:77]
	v_pk_add_f32 v[92:93], v[92:93], v[74:75]
	v_pk_add_f32 v[90:91], v[90:91], v[242:243]
	v_pk_add_f32 v[88:89], v[88:89], v[230:231]
	v_pk_add_f32 v[86:87], v[86:87], v[232:233]
	v_pk_add_f32 v[84:85], v[84:85], v[80:81]
	s_branch .LBB0_541
.Latt_nsub_b:
	v_pk_add_f32 v[96:97], v[208:209], v[96:97] op_sel_hi:[0,1]
	v_pk_add_f32 v[94:95], v[208:209], v[94:95] op_sel_hi:[0,1]
	v_pk_add_f32 v[92:93], v[208:209], v[92:93] op_sel_hi:[0,1]
	v_pk_add_f32 v[90:91], v[208:209], v[90:91] op_sel_hi:[0,1]
	v_pk_add_f32 v[88:89], v[208:209], v[88:89] op_sel_hi:[0,1]
	v_pk_add_f32 v[86:87], v[208:209], v[86:87] op_sel_hi:[0,1]
	v_pk_add_f32 v[84:85], v[208:209], v[84:85] op_sel_hi:[0,1]
	v_pk_add_f32 v[82:83], v[208:209], v[82:83] op_sel_hi:[0,1]
	s_nop 0
	s_branch .Latt_fast_b

; __global__ void __launch_bounds__(512) fwd_kernel(Args a) {
;     extern __shared__ __attribute__((aligned(16))) unsigned char lds_raw[];
	.amdhsa_kernel _Z10fwd_kernel4Args
		.amdhsa_group_segment_fixed_size 0
		.amdhsa_private_segment_fixed_size 0
		.amdhsa_kernarg_size 472
		.amdhsa_user_sgpr_count 2
		.amdhsa_user_sgpr_dispatch_ptr 0
		.amdhsa_user_sgpr_queue_ptr 0
		.amdhsa_user_sgpr_kernarg_segment_ptr 1
		.amdhsa_user_sgpr_dispatch_id 0
		.amdhsa_user_sgpr_kernarg_preload_length 0
		.amdhsa_user_sgpr_kernarg_preload_offset 0
		.amdhsa_user_sgpr_private_segment_size 0
		.amdhsa_uses_dynamic_stack 0
		.amdhsa_enable_private_segment 0
		.amdhsa_system_sgpr_workgroup_id_x 1
		.amdhsa_system_sgpr_workgroup_id_y 0
		.amdhsa_system_sgpr_workgroup_id_z 0
		.amdhsa_system_sgpr_workgroup_info 0
		.amdhsa_system_vgpr_workitem_id 2
		.amdhsa_next_free_vgpr 256
		.amdhsa_next_free_sgpr 102
		.amdhsa_accum_offset 256
		.amdhsa_reserve_vcc 1
		.amdhsa_float_round_mode_32 0
		.amdhsa_float_round_mode_16_64 0
		.amdhsa_float_denorm_mode_32 3
		.amdhsa_float_denorm_mode_16_64 3
		.amdhsa_dx10_clamp 1
		.amdhsa_ieee_mode 1
		.amdhsa_fp16_overflow 0
		.amdhsa_tg_split 0
		.amdhsa_exception_fp_ieee_invalid_op 0
		.amdhsa_exception_fp_denorm_src 0
		.amdhsa_exception_fp_ieee_div_zero 0
		.amdhsa_exception_fp_ieee_overflow 0
		.amdhsa_exception_fp_ieee_underflow 0
		.amdhsa_exception_fp_ieee_inexact 0
		.amdhsa_exception_int_div_zero 0
	.end_amdhsa_kernel
